# baseline (speedup 1.0000x reference)
; #define LAS __attribute__((address_space(3)))
; __device__ __forceinline__ unsigned pk2(float lo, float hi) { return f2bf(lo) | (f2bf(hi) << 16); }
; #define MFMA16(a, b, c) __builtin_amdgcn_mfma_f32_16x16x32_bf16((a), (b), (c), 0, 0, 0)
; template <int KIND, int MODE>
; __device__ __forceinline__ void scan_unit(Frame& F, int layer, int h, int vhalf, int grp) {
;     ...
;             for (int tt = 0; tt < 4; ++tt) { const int t = 16 * tt + li; f32x4 oi = (f32x4){0.f, 0.f, 0.f, 0.f}, oe = (f32x4){0.f, 0.f, 0.f, 0.f};
; #pragma unroll
;                 for (int ks = 0; ks < 2; ++ks) { const bf16x8 pb = *(const LAS bf16x8*)(PS + t * PST + 32 * ks + 8 * g); oi = MFMA16(vf[ks], pb, oi); }
; #pragma unroll
;                 for (int i = 0; i < NSL; ++i) { const u32x2 q0 = *(const LAS u32x2*)(QS + t * QST + 32 * i + 4 * g), q1 = *(const LAS u32x2*)(QS + t * QST + 32 * i + 16 + 4 * g);
;                     const bf16x8 qb = __builtin_bit_cast(bf16x8, ((u32x4){q0.x, q0.y, q1.x, q1.y})); oe = MFMA16(sf[i], qb, oe); }
;                 f32x4 o;
;                 if (KIND) { const float wi = X[128 + t]; float qn = wi * (((X[896 + t] + X[960 + t]) + (X[1024 + t] + X[1088 + t])) + ((X[1152 + t] + X[1216 + t]) + (X[1280 + t] + X[1344 + t])));
;                     qn += (X[640 + t] + X[704 + t]) + (X[768 + t] + X[832 + t]);
;                     const float inv = 1.0f / fmaxf(fabsf(qn), X[256 + t]); o = (oi + oe * wi) * inv; }
;                 else o = oi + oe;
;                 u32x2 ow; ow.x = pk2(o[0], o[1]); ow.y = pk2(o[2], o[3]); *(u32x2*)(yout + (size_t)(tb + t) * D) = ow;
;                 float sq = (o[0] * o[0] + o[1] * o[1]) + (o[2] * o[2] + o[3] * o[3]); sq += __shfl_xor(sq, 16); sq += __shfl_xor(sq, 32);
;                 if (g == 0) SSR[w * 64 + t] = sq;
;             }
.LBB0_538:
	s_or_b64 exec, exec, s[0:1]
	s_waitcnt lgkmcnt(0)
	ds_read_b128 v[108:111], v200
	ds_read_b128 v[112:115], v200 offset:64
	ds_read2_b64 v[208:211], v187 offset1:4
	ds_read2_b64 v[212:215], v187 offset0:8 offset1:12
	ds_read2_b64 v[216:219], v187 offset0:16 offset1:20
	ds_read2_b64 v[220:223], v187 offset0:24 offset1:28
	ds_read2_b64 v[236:239], v187 offset0:32 offset1:36
	ds_read2_b64 v[240:243], v187 offset0:40 offset1:44
	ds_read2_b64 v[244:247], v187 offset0:48 offset1:52
	ds_read2_b64 v[248:251], v187 offset0:56 offset1:60
	s_waitcnt lgkmcnt(6)
	v_mfma_f32_16x16x32_bf16 v[108:111], v[72:75], v[108:111], 0
	v_mfma_f32_16x16x32_bf16 v[208:211], v[76:79], v[208:211], 0
	v_mfma_f32_16x16x32_bf16 v[208:211], v[80:83], v[212:215], v[208:211]
	s_waitcnt lgkmcnt(5)
	v_mfma_f32_16x16x32_bf16 v[208:211], v[84:87], v[216:219], v[208:211]
	s_waitcnt lgkmcnt(4)
	v_mfma_f32_16x16x32_bf16 v[208:211], v[88:91], v[220:223], v[208:211]
	s_waitcnt lgkmcnt(3)
	v_mfma_f32_16x16x32_bf16 v[208:211], v[92:95], v[236:239], v[208:211]
	s_waitcnt lgkmcnt(2)
	v_mfma_f32_16x16x32_bf16 v[208:211], v[96:99], v[240:243], v[208:211]
	s_waitcnt lgkmcnt(1)
	v_mfma_f32_16x16x32_bf16 v[208:211], v[100:103], v[244:247], v[208:211]
	s_waitcnt lgkmcnt(0)
	v_mfma_f32_16x16x32_bf16 v[208:211], v[104:107], v[248:251], v[208:211]
	v_mfma_f32_16x16x32_bf16 v[108:111], v[68:71], v[112:115], v[108:111]
	ds_read2st64_b32 v[112:113], v188 offset0:2 offset1:4
	ds_read2st64_b32 v[114:115], v188 offset0:14 offset1:15
	ds_read2st64_b32 v[166:167], v188 offset0:16 offset1:17
	ds_read2st64_b32 v[212:213], v188 offset0:18 offset1:19
	ds_read2st64_b32 v[214:215], v188 offset0:20 offset1:21
	ds_read2st64_b32 v[216:217], v188 offset0:10 offset1:11
	ds_read2st64_b32 v[218:219], v188 offset0:12 offset1:13
	s_waitcnt lgkmcnt(0)
	v_add_f32_e32 v114, v114, v115
	v_add_f32_e32 v166, v166, v167
	v_add_f32_e32 v212, v212, v213
	v_add_f32_e32 v214, v214, v215
	v_mov_b32_e32 v115, v216
	v_mov_b32_e32 v167, v217
	v_mov_b32_e32 v213, v218
	v_mov_b32_e32 v215, v219
	v_pk_add_f32 v[114:115], v[114:115], v[166:167]
	v_pk_add_f32 v[166:167], v[212:213], v[214:215]
	v_max_f32_e32 v0, v113, v113
	v_pk_add_f32 v[114:115], v[114:115], v[166:167]
	s_nop 0
	v_fmac_f32_e32 v115, v112, v114
	v_max_f32_e64 v0, |v115|, v0
	v_div_scale_f32 v113, s[0:1], v0, v0, 1.0
	v_rcp_f32_e32 v114, v113
	s_nop 0
	v_fma_f32 v115, -v113, v114, 1.0
	v_fmac_f32_e32 v114, v115, v114
	v_div_scale_f32 v115, vcc, 1.0, v0, 1.0
	v_mul_f32_e32 v166, v115, v114
	v_fma_f32 v167, -v113, v166, v115
	v_fmac_f32_e32 v166, v167, v114
	v_fma_f32 v113, -v113, v166, v115
	v_div_fmas_f32 v113, v113, v114, v166
	v_div_fixup_f32 v0, v113, v0, 1.0
	v_pk_fma_f32 v[110:111], v[210:211], v[112:113], v[110:111] op_sel_hi:[1,0,1]
	v_pk_fma_f32 v[108:109], v[208:209], v[112:113], v[108:109] op_sel_hi:[1,0,1]
	v_pk_mul_f32 v[110:111], v[110:111], v[0:1] op_sel_hi:[1,0]
	v_pk_mul_f32 v[108:109], v[108:109], v[0:1] op_sel_hi:[1,0]
	v_and_b32_sdwa v113, v111, v224 dst_sel:DWORD dst_unused:UNUSED_PAD src0_sel:WORD_1 src1_sel:DWORD
	v_and_b32_sdwa v0, v110, v224 dst_sel:DWORD dst_unused:UNUSED_PAD src0_sel:WORD_1 src1_sel:DWORD
	v_add3_u32 v113, v111, v113, s81
	v_add3_u32 v0, v110, v0, s81
	v_and_b32_e32 v113, 0xffff0000, v113
	v_and_b32_sdwa v112, v108, v224 dst_sel:DWORD dst_unused:UNUSED_PAD src0_sel:WORD_1 src1_sel:DWORD
	v_or_b32_sdwa v113, v113, v0 dst_sel:DWORD dst_unused:UNUSED_PAD src0_sel:DWORD src1_sel:WORD_1
	v_mul_f32_e32 v0, v109, v109
	v_add3_u32 v112, v108, v112, s81
	v_fmac_f32_e32 v0, v108, v108
	v_mul_f32_e32 v108, v111, v111
	v_fmac_f32_e32 v108, v110, v110
	v_add_f32_e32 v0, v0, v108
	ds_bpermute_b32 v108, v128, v0
	v_and_b32_sdwa v114, v109, v224 dst_sel:DWORD dst_unused:UNUSED_PAD src0_sel:WORD_1 src1_sel:DWORD
	v_add3_u32 v114, v109, v114, s81
	v_and_b32_e32 v114, 0xffff0000, v114
	v_or_b32_sdwa v112, v114, v112 dst_sel:DWORD dst_unused:UNUSED_PAD src0_sel:DWORD src1_sel:WORD_1
	s_waitcnt lgkmcnt(0)
	v_add_f32_e32 v0, v0, v108
	ds_bpermute_b32 v108, v129, v0
	v_or_b32_e32 v114, s44, v186
	v_ashrrev_i32_e32 v115, 31, v114
	v_lshlrev_b64 v[114:115], 11, v[114:115]
	v_lshl_add_u64 v[114:115], v[2:3], 0, v[114:115]
	flat_store_dwordx2 v[114:115], v[112:113]
	s_and_saveexec_b64 s[0:1], s[12:13]
	s_cbranch_execz .LBB0_540
	s_waitcnt lgkmcnt(0)
	v_add_f32_e32 v0, v0, v108
	ds_write_b32 v185, v0 offset:64
; #define LAS __attribute__((address_space(3)))
; __device__ __forceinline__ unsigned pk2(float lo, float hi) { return f2bf(lo) | (f2bf(hi) << 16); }
; #define MFMA16(a, b, c) __builtin_amdgcn_mfma_f32_16x16x32_bf16((a), (b), (c), 0, 0, 0)
; template <int KIND, int MODE>
; __device__ __forceinline__ void scan_unit(Frame& F, int layer, int h, int vhalf, int grp) {
;     ...
;             for (int tt = 0; tt < 4; ++tt) { const int t = 16 * tt + li; f32x4 oi = (f32x4){0.f, 0.f, 0.f, 0.f}, oe = (f32x4){0.f, 0.f, 0.f, 0.f};
; #pragma unroll
;                 for (int ks = 0; ks < 2; ++ks) { const bf16x8 pb = *(const LAS bf16x8*)(PS + t * PST + 32 * ks + 8 * g); oi = MFMA16(vf[ks], pb, oi); }
; #pragma unroll
;                 for (int i = 0; i < NSL; ++i) { const u32x2 q0 = *(const LAS u32x2*)(QS + t * QST + 32 * i + 4 * g), q1 = *(const LAS u32x2*)(QS + t * QST + 32 * i + 16 + 4 * g);
;                     const bf16x8 qb = __builtin_bit_cast(bf16x8, ((u32x4){q0.x, q0.y, q1.x, q1.y})); oe = MFMA16(sf[i], qb, oe); }
;                 f32x4 o;
;                 if (KIND) { const float wi = X[128 + t]; float qn = wi * (((X[896 + t] + X[960 + t]) + (X[1024 + t] + X[1088 + t])) + ((X[1152 + t] + X[1216 + t]) + (X[1280 + t] + X[1344 + t])));
;                     qn += (X[640 + t] + X[704 + t]) + (X[768 + t] + X[832 + t]);
;                     const float inv = 1.0f / fmaxf(fabsf(qn), X[256 + t]); o = (oi + oe * wi) * inv; }
;                 else o = oi + oe;
;                 u32x2 ow; ow.x = pk2(o[0], o[1]); ow.y = pk2(o[2], o[3]); *(u32x2*)(yout + (size_t)(tb + t) * D) = ow;
;                 float sq = (o[0] * o[0] + o[1] * o[1]) + (o[2] * o[2] + o[3] * o[3]); sq += __shfl_xor(sq, 16); sq += __shfl_xor(sq, 32);
;                 if (g == 0) SSR[w * 64 + t] = sq;
;             }
.LBB0_540:
	s_or_b64 exec, exec, s[0:1]
	s_waitcnt lgkmcnt(0)
	ds_read_b128 v[108:111], v201
	ds_read_b128 v[112:115], v201 offset:64
	ds_read2_b64 v[208:211], v190 offset1:4
	ds_read2_b64 v[212:215], v190 offset0:8 offset1:12
	ds_read2_b64 v[216:219], v190 offset0:16 offset1:20
	ds_read2_b64 v[220:223], v190 offset0:24 offset1:28
	ds_read2_b64 v[236:239], v190 offset0:32 offset1:36
	ds_read2_b64 v[240:243], v190 offset0:40 offset1:44
	ds_read2_b64 v[244:247], v190 offset0:48 offset1:52
	ds_read2_b64 v[248:251], v190 offset0:56 offset1:60
	s_waitcnt lgkmcnt(6)
	v_mfma_f32_16x16x32_bf16 v[108:111], v[72:75], v[108:111], 0
	v_mfma_f32_16x16x32_bf16 v[208:211], v[76:79], v[208:211], 0
	v_mfma_f32_16x16x32_bf16 v[208:211], v[80:83], v[212:215], v[208:211]
	s_waitcnt lgkmcnt(5)
	v_mfma_f32_16x16x32_bf16 v[208:211], v[84:87], v[216:219], v[208:211]
	s_waitcnt lgkmcnt(4)
	v_mfma_f32_16x16x32_bf16 v[208:211], v[88:91], v[220:223], v[208:211]
	s_waitcnt lgkmcnt(3)
	v_mfma_f32_16x16x32_bf16 v[208:211], v[92:95], v[236:239], v[208:211]
	s_waitcnt lgkmcnt(2)
	v_mfma_f32_16x16x32_bf16 v[208:211], v[96:99], v[240:243], v[208:211]
	s_waitcnt lgkmcnt(1)
	v_mfma_f32_16x16x32_bf16 v[208:211], v[100:103], v[244:247], v[208:211]
	s_waitcnt lgkmcnt(0)
	v_mfma_f32_16x16x32_bf16 v[208:211], v[104:107], v[248:251], v[208:211]
	v_mfma_f32_16x16x32_bf16 v[108:111], v[68:71], v[112:115], v[108:111]
	ds_read2st64_b32 v[112:113], v191 offset0:2 offset1:4
	ds_read2st64_b32 v[114:115], v191 offset0:14 offset1:15
	ds_read2st64_b32 v[166:167], v191 offset0:16 offset1:17
	ds_read2st64_b32 v[212:213], v191 offset0:18 offset1:19
	ds_read2st64_b32 v[214:215], v191 offset0:20 offset1:21
	ds_read2st64_b32 v[216:217], v191 offset0:10 offset1:11
	ds_read2st64_b32 v[218:219], v191 offset0:12 offset1:13
	s_waitcnt lgkmcnt(0)
	v_add_f32_e32 v114, v114, v115
	v_add_f32_e32 v166, v166, v167
	v_add_f32_e32 v212, v212, v213
	v_add_f32_e32 v214, v214, v215
	v_mov_b32_e32 v115, v216
	v_mov_b32_e32 v167, v217
	v_mov_b32_e32 v213, v218
	v_mov_b32_e32 v215, v219
	v_pk_add_f32 v[114:115], v[114:115], v[166:167]
	v_pk_add_f32 v[166:167], v[212:213], v[214:215]
	v_max_f32_e32 v0, v113, v113
	v_pk_add_f32 v[114:115], v[114:115], v[166:167]
	s_nop 0
	v_fmac_f32_e32 v115, v112, v114
	v_max_f32_e64 v0, |v115|, v0
	v_div_scale_f32 v113, s[0:1], v0, v0, 1.0
	v_rcp_f32_e32 v114, v113
	s_nop 0
	v_fma_f32 v115, -v113, v114, 1.0
	v_fmac_f32_e32 v114, v115, v114
	v_div_scale_f32 v115, vcc, 1.0, v0, 1.0
	v_mul_f32_e32 v166, v115, v114
	v_fma_f32 v167, -v113, v166, v115
	v_fmac_f32_e32 v166, v167, v114
	v_fma_f32 v113, -v113, v166, v115
	v_div_fmas_f32 v113, v113, v114, v166
	v_div_fixup_f32 v0, v113, v0, 1.0
	v_pk_fma_f32 v[110:111], v[210:211], v[112:113], v[110:111] op_sel_hi:[1,0,1]
	v_pk_fma_f32 v[108:109], v[208:209], v[112:113], v[108:109] op_sel_hi:[1,0,1]
	v_pk_mul_f32 v[110:111], v[110:111], v[0:1] op_sel_hi:[1,0]
	v_pk_mul_f32 v[108:109], v[108:109], v[0:1] op_sel_hi:[1,0]
	v_and_b32_sdwa v113, v111, v224 dst_sel:DWORD dst_unused:UNUSED_PAD src0_sel:WORD_1 src1_sel:DWORD
	v_and_b32_sdwa v0, v110, v224 dst_sel:DWORD dst_unused:UNUSED_PAD src0_sel:WORD_1 src1_sel:DWORD
	v_add3_u32 v113, v111, v113, s81
	v_add3_u32 v0, v110, v0, s81
	v_and_b32_e32 v113, 0xffff0000, v113
	v_and_b32_sdwa v112, v108, v224 dst_sel:DWORD dst_unused:UNUSED_PAD src0_sel:WORD_1 src1_sel:DWORD
	v_or_b32_sdwa v113, v113, v0 dst_sel:DWORD dst_unused:UNUSED_PAD src0_sel:DWORD src1_sel:WORD_1
	v_mul_f32_e32 v0, v109, v109
	v_add3_u32 v112, v108, v112, s81
	v_fmac_f32_e32 v0, v108, v108
	v_mul_f32_e32 v108, v111, v111
	v_fmac_f32_e32 v108, v110, v110
	v_add_f32_e32 v0, v0, v108
	ds_bpermute_b32 v108, v128, v0
	v_and_b32_sdwa v114, v109, v224 dst_sel:DWORD dst_unused:UNUSED_PAD src0_sel:WORD_1 src1_sel:DWORD
	v_add3_u32 v114, v109, v114, s81
	v_and_b32_e32 v114, 0xffff0000, v114
	v_or_b32_sdwa v112, v114, v112 dst_sel:DWORD dst_unused:UNUSED_PAD src0_sel:DWORD src1_sel:WORD_1
	s_waitcnt lgkmcnt(0)
	v_add_f32_e32 v0, v0, v108
	ds_bpermute_b32 v108, v129, v0
	v_or_b32_e32 v114, s44, v189
	v_ashrrev_i32_e32 v115, 31, v114
	v_lshlrev_b64 v[114:115], 11, v[114:115]
	v_lshl_add_u64 v[114:115], v[2:3], 0, v[114:115]
	flat_store_dwordx2 v[114:115], v[112:113]
	s_and_saveexec_b64 s[0:1], s[12:13]
	s_cbranch_execz .LBB0_542
	s_waitcnt lgkmcnt(0)
	v_add_f32_e32 v0, v0, v108
	ds_write_b32 v185, v0 offset:128
